# UP epilogue: first tap-weight LDS reads issued with the first reads (before the exchange barrier)
# speedup vs baseline: 1.0073x; 1.0073x over previous
.Lnepia_nohalo:
	s_or_b64 exec, exec, s[8:9]
	s_waitcnt lgkmcnt(0)
	s_barrier
	s_cmp_eq_u32 s50, 0
	s_cbranch_scc1 .Lnepia_z0
	ds_read_b128 v[118:121], v227 offset:512
	ds_read_b128 v[122:125], v227 offset:1536
	s_branch .Lnepia_j0

.Lnepib_nohalo:
	s_or_b64 exec, exec, s[8:9]
	s_waitcnt lgkmcnt(0)
	s_barrier
	s_cmp_eq_u32 s54, 0
	s_cbranch_scc1 .Lnepib_z0
	ds_read_b128 v[118:121], v227 offset:512
	ds_read_b128 v[122:125], v227 offset:1536
	s_branch .Lnepib_j0
